# selected-block stream: stage header software-pipelined (next stage's block numbers and masks fetched one stage ahead into SGPRs, DMA addresses by scalar math, no LDS round trip between the stage barri
# speedup vs baseline: 1.0040x; 1.0040x over previous
; #define LAS __attribute__((address_space(3)))
; #define SS_ISSUE(t, slot) do { LAS unsigned char* d_ = lbase + (slot) * 2 * TILEB; const size_t gb_ = (size_t)rowfn(t) * 256 + goff; \
;         __builtin_amdgcn_global_load_lds((const unsigned*)((const char*)Kg + gb_), (LAS unsigned*)d_, 16, 0, 0); \
;         __builtin_amdgcn_global_load_lds((const unsigned*)((const char*)Vg + gb_), (LAS unsigned*)(d_ + TILEB), 16, 0, 0); } while (0)
; template <int NB, class RowFn, class Compute>
; DEV void stream_stages_dma(Frame& F, int n, const bf16* Kg, const bf16* Vg, RowFn rowfn, Compute compute) {
;     ...
; #pragma unroll
;     for (int b = 0; b < NB; ++b) if (b < n) SS_ISSUE(b, b);
;     for (int i0 = 0, st = 0; i0 < n; i0 += NB, st ^= 1) {
;         asm volatile("s_waitcnt vmcnt(0)" ::: "memory");
;         __builtin_amdgcn_s_barrier(); asm volatile("" ::: "memory");
; #pragma unroll
;         for (int b = 0; b < NB; ++b) if (i0 + NB + b < n) SS_ISSUE(i0 + NB + b, (st ^ 1) * NB + b);
;         const LAS unsigned char* cur = F.lds + st * NB * 2 * TILEB;
; #pragma unroll
;         for (int b = 0; b < NB; ++b) if (i0 + b < n) compute(i0 + b, cur + b * 2 * TILEB, cur + b * 2 * TILEB + TILEB);
;     }
; DEV void attn_unit_mfma(Frame& F, int qg, int kv) {
;     ...
;         const int j = lst[1 + i]; const unsigned byte = (msk[2 * j + (w >> 2)] >> (8 * (w & 3))) & 0xffu;
;         const bool a0 = (byte & 0xfu) != 0u, a1 = (byte & 0xf0u) != 0u;
.LBB0_1166:
	v_cmp_lt_i32_e32 vcc, v147, v205
	v_mov_b32_e32 v28, v19
	v_mov_b32_e32 v29, v19
	v_cndmask_b32_e32 v26, v139, v147, vcc
	v_cmp_lt_i32_e32 vcc, v145, v205
	v_lshlrev_b32_e32 v210, 2, v26
	v_mov_b32_e32 v27, v19
	v_cndmask_b32_e32 v26, v139, v145, vcc
	v_lshlrev_b32_e32 v211, 2, v26
	v_mov_b32_e32 v26, v19
	v_mov_b64_e32 v[32:33], v[28:29]
	v_mov_b64_e32 v[36:37], v[28:29]
	v_mov_b64_e32 v[40:41], v[28:29]
	v_mov_b64_e32 v[48:49], v[28:29]
	v_mov_b64_e32 v[52:53], v[28:29]
	v_mov_b64_e32 v[56:57], v[28:29]
	v_mov_b64_e32 v[64:65], v[28:29]
	v_mov_b64_e32 v[44:45], v[28:29]
	v_mov_b64_e32 v[60:61], v[28:29]
	v_lshlrev_b32_e64 v206, v196, 1
	v_lshlrev_b32_e64 v207, v196, 16
	v_not_b32_e32 v208, v20
	s_mov_b32 s28, 2
	v_or_b32_e32 v1, 3, v20
	v_or_b32_e32 v158, 2, v20
	v_lshlrev_b32_e32 v209, 7, v94
	s_mov_b32 s8, 0
	v_mov_b32_e32 v213, 0xff800000
	v_mov_b64_e32 v[30:31], v[26:27]
	v_mov_b64_e32 v[34:35], v[26:27]
	v_mov_b64_e32 v[38:39], v[26:27]
	v_mov_b64_e32 v[46:47], v[26:27]
	v_mov_b64_e32 v[50:51], v[26:27]
	v_mov_b64_e32 v[54:55], v[26:27]
	v_mov_b64_e32 v[62:63], v[26:27]
	v_mov_b64_e32 v[42:43], v[26:27]
	v_mov_b64_e32 v[58:59], v[26:27]
	v_mov_b32_e32 v212, 0xff800000
	v_mov_b32_e32 v66, s24
	ds_read_b32 v67, v66
	ds_read_b32 v68, v66 offset:4
	ds_read_b32 v69, v66 offset:8
	ds_read_b32 v73, v66 offset:12
	ds_read_b32 v74, v66 offset:16
	ds_read_b32 v75, v66 offset:20
	s_waitcnt lgkmcnt(0)
	v_lshl_add_u32 v70, v67, 3, s2
	v_lshl_add_u32 v71, v68, 3, s2
	v_lshl_add_u32 v72, v69, 3, s2
	ds_read_b32 v70, v70
	ds_read_b32 v71, v71
	ds_read_b32 v72, v72
	v_readfirstlane_b32 s98, v67
	v_readfirstlane_b32 s99, v68
	v_readfirstlane_b32 s100, v69
	v_readfirstlane_b32 s37, v73
	v_readfirstlane_b32 s38, v74
	v_readfirstlane_b32 s39, v75
	s_waitcnt lgkmcnt(0)
	v_readfirstlane_b32 s9, v70
	v_readfirstlane_b32 s10, v71
	v_readfirstlane_b32 s11, v72
	s_and_b32 s98, s98, 0xffff
	s_and_b32 s99, s99, 0xffff
	s_and_b32 s100, s100, 0xffff
	s_lshr_b32 s9, s9, s33
	s_and_b32 s9, s9, 0xff
	s_lshl_b32 s9, s9, 16
	s_or_b32 s98, s98, s9
	s_lshr_b32 s10, s10, s33
	s_and_b32 s10, s10, 0xff
	s_lshl_b32 s10, s10, 16
	s_or_b32 s99, s99, s10
	s_lshr_b32 s11, s11, s33
	s_and_b32 s11, s11, 0xff
	s_lshl_b32 s11, s11, 16
	s_or_b32 s100, s100, s11
.LBB0_1167:
	s_waitcnt vmcnt(0)
	s_barrier
	s_xor_b32 s25, s8, 1
	s_mul_i32 s9, s25, 0xc000
	s_add_i32 s9, s51, s9
	s_add_i32 s26, s28, 3
	s_lshl_b32 s10, s37, 3
	s_lshl_b32 s11, s38, 3
	s_lshl_b32 s12, s39, 3
	s_add_i32 s10, s10, s2
	s_add_i32 s11, s11, s2
	s_add_i32 s12, s12, s2
	v_mov_b32_e32 v70, s10
	v_mov_b32_e32 v71, s11
	v_mov_b32_e32 v72, s12
	v_mov_b32_e32 v66, s24
	ds_read_b32 v70, v70
	ds_read_b32 v71, v71
	ds_read_b32 v72, v72
	ds_read_b32 v73, v66 offset:24
	ds_read_b32 v74, v66 offset:28
	ds_read_b32 v75, v66 offset:32
	s_add_i32 s10, s28, 1
	s_cmp_ge_i32 s10, s23
	s_cbranch_scc1 .Lmy_sel_dma_done
	s_lshl_b32 s10, s37, 14
	s_add_u32 s12, s92, s10
	s_addc_u32 s13, s93, 0
	s_add_u32 s14, s48, s10
	s_addc_u32 s15, s49, 0
	s_mov_b32 m0, s9
	s_nop 0
	global_load_lds_dwordx4 v156, s[12:13]
	s_add_i32 m0, s9, 0x2000
	s_nop 0
	global_load_lds_dwordx4 v156, s[14:15]
	s_add_i32 s10, s28, 2
	s_cmp_ge_i32 s10, s23
	s_cbranch_scc1 .Lmy_sel_dma_done
	s_lshl_b32 s10, s38, 14
	s_add_u32 s12, s92, s10
	s_addc_u32 s13, s93, 0
	s_add_u32 s14, s48, s10
	s_addc_u32 s15, s49, 0
	s_add_i32 m0, s9, 0x4000
	s_nop 0
	global_load_lds_dwordx4 v156, s[12:13]
	s_add_i32 m0, s9, 0x6000
	s_nop 0
	global_load_lds_dwordx4 v156, s[14:15]
	s_cmp_ge_i32 s26, s23
	s_cbranch_scc1 .Lmy_sel_dma_done
	s_lshl_b32 s10, s39, 14
	s_add_u32 s12, s92, s10
	s_addc_u32 s13, s93, 0
	s_add_u32 s14, s48, s10
	s_addc_u32 s15, s49, 0
	s_add_i32 m0, s9, 0x8000
	s_nop 0
	global_load_lds_dwordx4 v156, s[12:13]
	s_add_i32 m0, s9, 0xa000
	s_nop 0
	global_load_lds_dwordx4 v156, s[14:15]
.Lmy_sel_dma_done:
	s_waitcnt lgkmcnt(0)
	v_readfirstlane_b32 s9, v70
	v_readfirstlane_b32 s10, v71
	v_readfirstlane_b32 s11, v72
	s_and_b32 s34, s37, 0xffff
	s_lshr_b32 s9, s9, s33
	s_and_b32 s9, s9, 0xff
	s_lshl_b32 s9, s9, 16
	s_or_b32 s34, s34, s9
	s_and_b32 s35, s38, 0xffff
	s_lshr_b32 s10, s10, s33
	s_and_b32 s10, s10, 0xff
	s_lshl_b32 s10, s10, 16
	s_or_b32 s35, s35, s10
	s_and_b32 s36, s39, 0xffff
	s_lshr_b32 s11, s11, s33
	s_and_b32 s11, s11, 0xff
	s_lshl_b32 s11, s11, 16
	s_or_b32 s36, s36, s11
	v_readfirstlane_b32 s37, v73
	v_readfirstlane_b32 s38, v74
	v_readfirstlane_b32 s39, v75
	s_lshr_b32 s9, s98, 16
	s_cmp_lg_u32 s9, 0
	s_cselect_b32 s9, 1, 0
	s_lshr_b32 s10, s99, 16
	s_cmp_lg_u32 s10, 0
	s_cselect_b32 s10, 1, 0
	s_lshr_b32 s11, s100, 16
	s_cmp_lg_u32 s11, 0
	s_cselect_b32 s11, 1, 0
	s_add_i32 s12, s28, -1
	s_cmp_lt_i32 s12, s23
	s_cselect_b32 s10, s10, 0
	s_cmp_lt_i32 s28, s23
	s_cselect_b32 s11, s11, 0
	s_add_i32 s9, s9, s10
	s_add_i32 s9, s9, s11
	s_cmp_ge_u32 s9, 3
	s_cbranch_scc0 .Lmy_sel_p2
	s_setprio 2
	s_branch .Lmy_sel_pd

; #define LAS __attribute__((address_space(3)))
; #define SS_ISSUE(t, slot) do { LAS unsigned char* d_ = lbase + (slot) * 2 * TILEB; const size_t gb_ = (size_t)rowfn(t) * 256 + goff; \
;         __builtin_amdgcn_global_load_lds((const unsigned*)((const char*)Kg + gb_), (LAS unsigned*)d_, 16, 0, 0); \
;         __builtin_amdgcn_global_load_lds((const unsigned*)((const char*)Vg + gb_), (LAS unsigned*)(d_ + TILEB), 16, 0, 0); } while (0)
; template <int NB, class RowFn, class Compute>
; DEV void stream_stages_dma(Frame& F, int n, const bf16* Kg, const bf16* Vg, RowFn rowfn, Compute compute) {
;     ...
;     for (int i0 = 0, st = 0; i0 < n; i0 += NB, st ^= 1) {
;         asm volatile("s_waitcnt vmcnt(0)" ::: "memory");
;         __builtin_amdgcn_s_barrier(); asm volatile("" ::: "memory");
; #pragma unroll
;         for (int b = 0; b < NB; ++b) if (i0 + NB + b < n) SS_ISSUE(i0 + NB + b, (st ^ 1) * NB + b);
;         const LAS unsigned char* cur = F.lds + st * NB * 2 * TILEB;
; #pragma unroll
;         for (int b = 0; b < NB; ++b) if (i0 + b < n) compute(i0 + b, cur + b * 2 * TILEB, cur + b * 2 * TILEB + TILEB);
;     }
.LBB0_1248:
	s_add_i32 s24, s24, 12
	s_add_i32 s8, s26, -2
	s_cmp_ge_i32 s8, s23
	s_cbranch_scc1 .LBB0_1257
	s_mov_b32 s98, s34
	s_mov_b32 s99, s35
	s_mov_b32 s100, s36
	s_mov_b32 s28, s26
	s_mov_b32 s8, s25
	s_branch .LBB0_1167
